# combined: P2 mixer loads spread into compute + false vmcnt drains removed + gain loads hoisted; GEMM stage tiles re-laid out to full-line DMAs
# baseline (speedup 1.0000x reference)
; #define LAS __attribute__((address_space(3)))
; #define ATT_LOADKV(b_, blk_, kb_, h_) do { const bf16_t* kp_ = A.Z + ((size_t)(b_) * SEQ + (size_t)((blk_) - 1 + (kb_)) * 128 + skey) * INW + O_K + ((h_) >> 2) * 128 + 8 * spart; \
;         _Pragma("unroll") for (int i = 0; i < 4; ++i) { kr[i] = *(const u32x4*)(kp_ + 32 * i); vr[i] = *(const u32x4*)(kp_ + (O_V - O_K) + 32 * i); } } while (0)
; #define ATT_LOADQ(b_, blk_, h_) do { const bf16_t* qp_ = A.Z + ((size_t)(b_) * SEQ + (size_t)(blk_) * 128 + arow) * INW + (h_) * 128 + 8 * fq; \
;         _Pragma("unroll") for (int s = 0; s < 4; ++s) qraw[s] = *(const u32x4*)(qp_ + 32 * s); } while (0)
; __device__ __forceinline__ void conv_load(const ConvJob& J, int idx, f32x4 (&v)[8], int lane) {
;     const bool second = idx >= 32768; const int r = idx & 32767;
;     const float* W = second ? J.w2 : J.w1; const int N = second ? D : FF, nb = second ? 128 : 512;
;     const int k0 = 64 * (r / nb), n0 = 32 * (r % nb);
;     const float* p = W + (size_t)(k0 + 8 * (lane >> 3)) * N + n0 + 4 * (lane & 7);
; #pragma unroll
;     for (int i = 0; i < 8; ++i) v[i] = __builtin_nontemporal_load((const f32x4*)(p + (size_t)i * N));
; __device__ __forceinline__ void attn_stream(LAS unsigned char* lds, const MixArgs& A, ConvJob& J, int vcu, int G, int tid, int wid, int lane) {
;     ...
;         if (nvalid) { ATT_LOADKV(nb_, nblk, nkb, nh); if (nfirst) ATT_LOADQ(nb_, nblk, nh); }
;         f32x4 cv[8]; const int cidx = J.next; const bool cdo = cidx < CONV_BLOCKS;
;         if (cdo) conv_load(J, cidx, cv, lane);
;         LAS unsigned char* kbase = lds + buf * KV_BUF + K_OFF; LAS unsigned char* vbase = lds + buf * KV_BUF + V_OFF;
;         f32x4 sacc[8];
; #pragma unroll
;         for (int kt = 0; kt < 8; ++kt) { sacc[kt] = (f32x4){0.f, 0.f, 0.f, 0.f};
; #pragma unroll
;             for (int s = 0; s < 4; ++s) { const bf16x8 a = *(const LAS bf16x8*)(kbase + (16 * kt + fr) * KSTR + (32 * s + 8 * fq) * 2);
;                 sacc[kt] = __builtin_amdgcn_mfma_f32_16x16x32_bf16(a, qf[s], sacc[kt], 0, 0, 0); } }
.LBB0_163:
	s_xor_b64 s[70:71], s[10:11], -1
	s_and_b64 vcc, exec, s[70:71]
	s_ashr_i32 s67, s66, 31
	s_lshl_b64 s[72:73], s[66:67], 12
	s_add_i32 s67, s90, s68
	s_add_i32 s94, s67, -1
	s_ashr_i32 s95, s94, 31
	s_lshl_b64 s[94:95], s[94:95], 7
	v_mov_b32_e32 v1, s73
	v_or_b32_e32 v0, s72, v148
	v_lshl_add_u64 v[0:1], v[0:1], 0, s[94:95]
	v_mov_b64_e32 v[2:3], s[18:19]
	v_mad_u64_u32 v[2:3], s[94:95], v0, s83, v[2:3]
	s_lshl_b32 s67, s91, 6
	v_mad_i32_i24 v3, v1, s83, v3
	s_and_b32 s94, s67, 0x300
	s_mov_b32 s95, s59
	v_lshl_add_u64 v[0:1], v[2:3], 0, s[94:95]
	v_lshl_add_u64 v[0:1], v[0:1], 0, v[156:157]
	v_add_co_u32_e32 v4, vcc, 0x1000, v0
	v_lshl_add_u64 v[44:45], v[0:1], 0, s[60:61]
	v_addc_co_u32_e32 v5, vcc, 0, v1, vcc
	s_andn2_b64 vcc, exec, s[44:45]
	s_cbranch_vccnz .LBB0_166
	s_ashr_i32 s69, s68, 31
	s_lshl_b64 s[94:95], s[68:69], 7
	s_add_u32 s72, s94, s72
	s_addc_u32 s73, s95, s73
	v_lshl_add_u64 v[12:13], s[72:73], 0, v[150:151]
	v_mov_b64_e32 v[14:15], s[18:19]
	v_mad_u64_u32 v[14:15], s[72:73], v12, s83, v[14:15]
	v_mad_i32_i24 v15, v13, s83, v15
	s_lshl_b32 s72, s91, 8
	s_mov_b32 s73, s59
	v_lshl_add_u64 v[12:13], v[14:15], 0, s[72:73]
	v_lshlrev_b32_e32 v14, 1, v153
	v_mov_b32_e32 v15, v157
	v_lshl_add_u64 v[32:33], v[12:13], 0, v[14:15]
	global_load_dwordx4 v[12:15], v[32:33], off
	global_load_dwordx4 v[16:19], v[32:33], off offset:64
	global_load_dwordx4 v[24:27], v[32:33], off offset:128
	s_nop 0
	global_load_dwordx4 v[32:35], v[32:33], off offset:192
.LBB0_166:
	s_cmp_lt_i32 s81, 0x10000
	s_cselect_b64 s[72:73], -1, 0
	s_cmp_gt_i32 s81, 0xffff
	s_and_b32 s67, s81, 0x7fff
	s_cmpk_gt_i32 s81, 0x7fff
	s_cselect_b32 s69, s27, s25
	s_cselect_b32 s93, s26, s24
	v_mov_b32_e32 v49, s69
	s_cselect_b32 s69, 7, 9
	v_mov_b32_e32 v48, s93
	s_cselect_b32 s93, s85, 0x1ff
	s_cselect_b32 s96, 12, 14
	s_lshr_b32 s67, s67, s69
	v_lshl_or_b32 v50, s67, 6, v158
	v_mov_b32_e32 v51, v157
	s_and_b32 s67, s93, s81
	v_lshlrev_b64 v[50:51], s96, v[50:51]
	v_lshl_add_u64 v[48:49], v[50:51], 2, v[48:49]
	s_lshl_b32 s94, s67, 7
	s_mov_b32 s95, s59
	v_lshl_add_u64 v[48:49], v[48:49], 0, s[94:95]
	v_lshlrev_b32_e32 v50, 2, v160
	v_mov_b32_e32 v51, v157
	v_lshl_add_u64 v[72:73], v[48:49], 0, v[50:51]
	s_lshl_b64 s[94:95], 1, s96
	v_lshl_add_u64 v[52:53], s[94:95], 2, v[72:73]
	s_lshl_b64 s[94:95], 2, s96
	v_lshl_add_u64 v[56:57], s[94:95], 2, v[72:73]
	s_lshl_b64 s[94:95], 3, s96
	v_lshl_add_u64 v[60:61], s[94:95], 2, v[72:73]
	s_lshl_b64 s[94:95], 4, s96
	v_lshl_add_u64 v[64:65], s[94:95], 2, v[72:73]
	s_lshl_b64 s[94:95], 5, s96
	v_lshl_add_u64 v[68:69], s[94:95], 2, v[72:73]
	s_lshl_b64 s[94:95], 6, s96
	v_lshl_add_u64 v[74:75], s[94:95], 2, v[72:73]
	s_lshl_b64 s[94:95], 7, s96
	v_lshl_add_u64 v[76:77], s[94:95], 2, v[72:73]
.LBB0_168:
	s_mul_i32 s67, s88, 0x10800
	s_add_i32 s67, s67, 0
	v_add3_u32 v172, s67, v220, v222
	s_waitcnt lgkmcnt(0)
	ds_read_b128 v[128:131], v172
	ds_read_b128 v[132:135], v172 offset:64
	s_cmp_lg_u32 s63, s65
	s_waitcnt lgkmcnt(1)
	v_mfma_f32_16x16x32_bf16 v[128:131], v[128:131], v[80:83], 0
	ds_read_b128 v[168:171], v172 offset:30528
	s_waitcnt lgkmcnt(1)
	v_mfma_f32_16x16x32_bf16 v[128:131], v[132:135], v[84:87], v[128:131]
	global_load_dwordx4 v[0:3], v[44:45], off offset:64
	ds_read_b128 v[132:135], v172 offset:128
	s_waitcnt lgkmcnt(0)
	v_mfma_f32_16x16x32_bf16 v[128:131], v[132:135], v[88:91], v[128:131]
	ds_read_b128 v[132:135], v172 offset:192
	s_waitcnt lgkmcnt(0)
	v_mfma_f32_16x16x32_bf16 v[174:177], v[132:135], v[92:95], v[128:131]
	s_nop 4
	ds_read_b128 v[128:131], v172 offset:4352
	ds_read_b128 v[132:135], v172 offset:4416
	s_waitcnt lgkmcnt(1)
	v_mfma_f32_16x16x32_bf16 v[128:131], v[128:131], v[80:83], 0
	s_waitcnt lgkmcnt(0)
	v_mfma_f32_16x16x32_bf16 v[128:131], v[132:135], v[84:87], v[128:131]
	global_load_dwordx4 v[8:11], v[44:45], off offset:128
	ds_read_b128 v[132:135], v172 offset:4480
	s_waitcnt lgkmcnt(0)
	v_mfma_f32_16x16x32_bf16 v[128:131], v[132:135], v[88:91], v[128:131]
	ds_read_b128 v[132:135], v172 offset:4544
	s_waitcnt lgkmcnt(0)
	v_mfma_f32_16x16x32_bf16 v[180:183], v[132:135], v[92:95], v[128:131]
	s_nop 4
	ds_read_b128 v[128:131], v172 offset:8704
	ds_read_b128 v[132:135], v172 offset:8768
	s_waitcnt lgkmcnt(1)
	v_mfma_f32_16x16x32_bf16 v[128:131], v[128:131], v[80:83], 0
	s_waitcnt lgkmcnt(0)
	v_mfma_f32_16x16x32_bf16 v[128:131], v[132:135], v[84:87], v[128:131]
	global_load_dwordx4 v[36:39], v[44:45], off offset:1088
	ds_read_b128 v[132:135], v172 offset:8832
	s_waitcnt lgkmcnt(0)
	v_mfma_f32_16x16x32_bf16 v[128:131], v[132:135], v[88:91], v[128:131]
	ds_read_b128 v[132:135], v172 offset:8896
	s_waitcnt lgkmcnt(0)
	v_mfma_f32_16x16x32_bf16 v[184:187], v[132:135], v[92:95], v[128:131]
	s_nop 4
	ds_read_b128 v[128:131], v172 offset:13056
	ds_read_b128 v[132:135], v172 offset:13120
	s_waitcnt lgkmcnt(1)
	v_mfma_f32_16x16x32_bf16 v[128:131], v[128:131], v[80:83], 0
	s_waitcnt lgkmcnt(0)
	v_mfma_f32_16x16x32_bf16 v[128:131], v[132:135], v[84:87], v[128:131]
	global_load_dwordx4 v[40:43], v[44:45], off offset:1152
	ds_read_b128 v[132:135], v172 offset:13184
	s_waitcnt lgkmcnt(0)
	v_mfma_f32_16x16x32_bf16 v[128:131], v[132:135], v[88:91], v[128:131]
	ds_read_b128 v[132:135], v172 offset:13248
	s_waitcnt lgkmcnt(0)
	v_mfma_f32_16x16x32_bf16 v[144:147], v[132:135], v[92:95], v[128:131]
	s_nop 4
	ds_read_b128 v[128:131], v172 offset:17408
	ds_read_b128 v[132:135], v172 offset:17472
	s_waitcnt lgkmcnt(1)
	v_mfma_f32_16x16x32_bf16 v[128:131], v[128:131], v[80:83], 0
	s_waitcnt lgkmcnt(0)
	v_mfma_f32_16x16x32_bf16 v[128:131], v[132:135], v[84:87], v[128:131]
	global_load_dwordx4 v[20:23], v[44:45], off offset:1024
	ds_read_b128 v[132:135], v172 offset:17536
	s_waitcnt lgkmcnt(0)
; #define LAS __attribute__((address_space(3)))
; __device__ __forceinline__ void attn_stream(LAS unsigned char* lds, const MixArgs& A, ConvJob& J, int vcu, int G, int tid, int wid, int lane) {
;     ...
;         for (int kt = 0; kt < 8; ++kt) { sacc[kt] = (f32x4){0.f, 0.f, 0.f, 0.f};
; #pragma unroll
;             for (int s = 0; s < 4; ++s) { const bf16x8 a = *(const LAS bf16x8*)(kbase + (16 * kt + fr) * KSTR + (32 * s + 8 * fq) * 2);
;                 sacc[kt] = __builtin_amdgcn_mfma_f32_16x16x32_bf16(a, qf[s], sacc[kt], 0, 0, 0); } }
;         float bm = -1e30f;
;         {
;             const LAS float* btp = bt + (kb * 128 + 4 * fq - arow + 127);
;             const LAS f32x4* rnp = (const LAS f32x4*)(lds + RN_OFF) + buf * 32 + fq;
; #pragma unroll
;             for (int kt = 0; kt < 8; ++kt) { const f32x4 rk = rnp[4 * kt];
; #pragma unroll
;                 for (int j = 0; j < 4; ++j) { const float v = sacc[kt][j] * rk[j] + btp[16 * kt + j]; sacc[kt][j] = v; bm = fmaxf(bm, v); } }
;         }
;         bm = fmaxf(bm, __shfl_xor(bm, 16)); bm = fmaxf(bm, __shfl_xor(bm, 32));
	v_mfma_f32_16x16x32_bf16 v[128:131], v[132:135], v[88:91], v[128:131]
	ds_read_b128 v[132:135], v172 offset:17600
	s_waitcnt lgkmcnt(0)
	v_mfma_f32_16x16x32_bf16 v[140:143], v[132:135], v[92:95], v[128:131]
	s_nop 4
	ds_read_b128 v[128:131], v172 offset:21760
	ds_read_b128 v[132:135], v172 offset:21824
	s_waitcnt lgkmcnt(1)
	v_mfma_f32_16x16x32_bf16 v[128:131], v[128:131], v[80:83], 0
	s_waitcnt lgkmcnt(0)
	v_mfma_f32_16x16x32_bf16 v[128:131], v[132:135], v[84:87], v[128:131]
	global_load_dwordx4 v[28:31], v[44:45], off offset:192
	ds_read_b128 v[132:135], v172 offset:21888
	s_waitcnt lgkmcnt(0)
	v_mfma_f32_16x16x32_bf16 v[128:131], v[132:135], v[88:91], v[128:131]
	ds_read_b128 v[132:135], v172 offset:21952
	s_waitcnt lgkmcnt(0)
	v_mfma_f32_16x16x32_bf16 v[136:139], v[132:135], v[92:95], v[128:131]
	s_nop 4
	ds_read_b128 v[128:131], v172 offset:26112
	ds_read_b128 v[132:135], v172 offset:26176
	s_waitcnt lgkmcnt(1)
	v_mfma_f32_16x16x32_bf16 v[128:131], v[128:131], v[80:83], 0
	s_waitcnt lgkmcnt(0)
	v_mfma_f32_16x16x32_bf16 v[128:131], v[132:135], v[84:87], v[128:131]
	global_load_dwordx4 v[4:7], v[4:5], off
	ds_read_b128 v[132:135], v172 offset:26240
	s_waitcnt lgkmcnt(0)
	v_mfma_f32_16x16x32_bf16 v[128:131], v[132:135], v[88:91], v[128:131]
	ds_read_b128 v[132:135], v172 offset:26304
	s_waitcnt lgkmcnt(0)
	v_mfma_f32_16x16x32_bf16 v[132:135], v[132:135], v[92:95], v[128:131]
	s_nop 4
	ds_read_b128 v[128:131], v172 offset:30464
	s_waitcnt lgkmcnt(0)
	v_mfma_f32_16x16x32_bf16 v[128:131], v[128:131], v[80:83], 0
	v_mfma_f32_16x16x32_bf16 v[128:131], v[168:171], v[84:87], v[128:131]
	global_load_dwordx4 v[44:47], v[44:45], off offset:1216
	ds_read_b128 v[168:171], v172 offset:30592
	s_waitcnt lgkmcnt(0)
	v_mfma_f32_16x16x32_bf16 v[128:131], v[168:171], v[88:91], v[128:131]
	ds_read_b128 v[168:171], v172 offset:30656
	s_waitcnt lgkmcnt(0)
	v_mfma_f32_16x16x32_bf16 v[128:131], v[168:171], v[92:95], v[128:131]
	v_lshl_add_u32 v169, s88, 9, v214
	v_lshl_add_u32 v168, s63, 9, v223
	ds_read_b128 v[188:191], v169
	ds_read2_b32 v[172:173], v168 offset0:127 offset1:128
	ds_read2_b32 v[170:171], v168 offset0:129 offset1:130
	s_waitcnt lgkmcnt(1)
	v_fma_f32 v172, v174, v188, v172
	v_fmac_f32_e32 v173, v175, v189
	v_max3_f32 v174, v172, s86, v173
	s_waitcnt lgkmcnt(0)
	v_fma_f32 v237, v176, v190, v170
	v_fmac_f32_e32 v171, v177, v191
	v_max3_f32 v170, v174, v237, v171
	ds_read_b128 v[174:177], v169 offset:64
	ds_read2_b32 v[178:179], v168 offset0:143 offset1:144
	s_waitcnt lgkmcnt(0)
	global_load_dwordx4 v[48:51], v[72:73], off nt
	v_fma_f32 v178, v180, v174, v178
	v_fmac_f32_e32 v179, v181, v175
	ds_read2_b32 v[180:181], v168 offset0:145 offset1:146
	v_max3_f32 v170, v170, v178, v179
	s_waitcnt lgkmcnt(0)
	v_fma_f32 v180, v182, v176, v180
	v_fmac_f32_e32 v181, v183, v177
	ds_read_b128 v[188:191], v169 offset:128
	ds_read2_b32 v[176:177], v168 offset0:159 offset1:160
	ds_read2_b32 v[174:175], v168 offset0:161 offset1:162
	v_max3_f32 v170, v170, v180, v181
	s_waitcnt lgkmcnt(1)
	v_fma_f32 v176, v184, v188, v176
	v_fmac_f32_e32 v177, v185, v189
	s_waitcnt lgkmcnt(0)
	v_fma_f32 v174, v186, v190, v174
	v_fmac_f32_e32 v175, v187, v191
	ds_read_b128 v[182:185], v169 offset:192
	ds_read2_b32 v[186:187], v168 offset0:175 offset1:176
	ds_read2_b32 v[188:189], v168 offset0:177 offset1:178
	v_max3_f32 v170, v170, v176, v177
	v_max3_f32 v170, v170, v174, v175
	s_waitcnt lgkmcnt(1)
	v_fma_f32 v186, v144, v182, v186
	v_fmac_f32_e32 v187, v145, v183
	v_max3_f32 v144, v170, v186, v187
	global_load_dwordx4 v[52:55], v[52:53], off nt
	s_waitcnt lgkmcnt(0)
	v_fma_f32 v188, v146, v184, v188
	v_fmac_f32_e32 v189, v147, v185
	v_max3_f32 v170, v144, v188, v189
	ds_read_b128 v[144:147], v169 offset:256
	ds_read2_b32 v[184:185], v168 offset0:191 offset1:192
	ds_read2_b32 v[182:183], v168 offset0:193 offset1:194
	s_waitcnt lgkmcnt(1)
	v_fma_f32 v184, v140, v144, v184
	v_fmac_f32_e32 v185, v141, v145
	v_max3_f32 v140, v170, v184, v185
	s_waitcnt lgkmcnt(0)
	v_fma_f32 v182, v142, v146, v182
	v_fmac_f32_e32 v183, v143, v147
	v_max3_f32 v144, v140, v182, v183
	ds_read_b128 v[140:143], v169 offset:320
	ds_read2_b32 v[194:195], v168 offset0:207 offset1:208
	ds_read2_b32 v[196:197], v168 offset0:209 offset1:210
	s_waitcnt lgkmcnt(1)
	v_fma_f32 v194, v136, v140, v194
	v_fmac_f32_e32 v195, v137, v141
	v_max3_f32 v136, v144, v194, v195
	s_waitcnt lgkmcnt(0)
	v_fma_f32 v196, v138, v142, v196
	v_fmac_f32_e32 v197, v139, v143
	v_max3_f32 v140, v136, v196, v197
	global_load_dwordx4 v[56:59], v[56:57], off nt
	ds_read_b128 v[136:139], v169 offset:384
	ds_read2_b32 v[192:193], v168 offset0:223 offset1:224
	ds_read2_b32 v[190:191], v168 offset0:225 offset1:226
	s_waitcnt lgkmcnt(1)
	v_fma_f32 v192, v132, v136, v192
	v_fmac_f32_e32 v193, v133, v137
	v_max3_f32 v132, v140, v192, v193
	s_waitcnt lgkmcnt(0)
	v_fma_f32 v190, v134, v138, v190
	v_fmac_f32_e32 v191, v135, v139
	v_max3_f32 v136, v132, v190, v191
	ds_read_b128 v[132:135], v169 offset:448
	ds_read2_b32 v[198:199], v168 offset0:239 offset1:240
	ds_read2_b32 v[200:201], v168 offset0:241 offset1:242
	s_waitcnt lgkmcnt(1)
	v_fma_f32 v198, v128, v132, v198
	v_fmac_f32_e32 v199, v129, v133
	v_max3_f32 v128, v136, v198, v199
	s_waitcnt lgkmcnt(0)
	v_fma_f32 v168, v130, v134, v200
	v_fmac_f32_e32 v201, v131, v135
	v_max3_f32 v128, v128, v168, v201
	ds_bpermute_b32 v129, v218, v128
	s_waitcnt lgkmcnt(0)
	v_max_f32_e32 v129, v129, v129
	v_max_f32_e32 v128, v128, v129
	global_load_dwordx4 v[60:63], v[60:61], off nt
	ds_bpermute_b32 v129, v219, v128
	s_waitcnt lgkmcnt(0)
; __device__ __forceinline__ unsigned cvt_pk_bf16(float lo, float hi) { unsigned r; asm volatile("v_cvt_pk_bf16_f32 %0, %1, %2" : "=v"(r) : "v"(lo), "v"(hi)); return r; }
; __device__ __forceinline__ void attn_stream(LAS unsigned char* lds, const MixArgs& A, ConvJob& J, int vcu, int G, int tid, int wid, int lane) {
;     ...
;         const float mnew = fmaxf(mrun, bm), alpha = __builtin_amdgcn_exp2f((mrun - mnew) * L2E);
;         mrun = mnew; lpart *= alpha;
; #pragma unroll
;         for (int c = 0; c < 8; ++c) oacc[c] = oacc[c] * alpha;
;         const float moff = mnew * L2E;
;         bf16x8 pf[4];
; #pragma unroll
;         for (int ks = 0; ks < 4; ++ks) { float p[8];
; #pragma unroll
;             for (int j = 0; j < 4; ++j) { p[j] = __builtin_amdgcn_exp2f(sacc[2 * ks][j] * L2E - moff); p[4 + j] = __builtin_amdgcn_exp2f(sacc[2 * ks + 1][j] * L2E - moff); }
;             lpart += ((p[0] + p[1]) + (p[2] + p[3])) + ((p[4] + p[5]) + (p[6] + p[7]));
;             u32x4 w; w.x = cvt_pk_bf16(p[0], p[1]); w.y = cvt_pk_bf16(p[2], p[3]); w.z = cvt_pk_bf16(p[4], p[5]); w.w = cvt_pk_bf16(p[6], p[7]);
;             pf[ks] = __builtin_bit_cast(bf16x8, w); }
; #pragma unroll
;         for (int ks = 0; ks < 4; ++ks)
; #pragma unroll
;             for (int c = 0; c < 8; ++c) { const bf16x8 a = tr_frag(vbase, 32 * ks, c, lane);
;                 oacc[c] = __builtin_amdgcn_mfma_f32_16x16x32_bf16(a, pf[ks], oacc[c], 0, 0, 0); }
	v_max3_f32 v169, v167, v128, v129
	v_sub_f32_e32 v128, v167, v169
	v_mul_f32_e32 v128, 0x3fb8aa3b, v128
	v_exp_f32_e32 v170, v128
	s_nop 0
	v_pk_mul_f32 v[144:145], v[108:109], v[170:171] op_sel_hi:[1,0]
	v_pk_mul_f32 v[108:109], v[120:121], v[170:171] op_sel_hi:[1,0]
	v_pk_mul_f32 v[120:121], v[168:169], s[42:43] op_sel_hi:[1,0]
	v_pk_mul_f32 v[134:135], v[98:99], v[170:171] op_sel_hi:[1,0]
	v_pk_mul_f32 v[132:133], v[96:97], v[170:171] op_sel_hi:[1,0]
	v_pk_mul_f32 v[130:131], v[102:103], v[170:171] op_sel_hi:[1,0]
	v_pk_mul_f32 v[128:129], v[100:101], v[170:171] op_sel_hi:[1,0]
	v_fma_f32 v96, v172, s42, -v121
	v_fma_f32 v98, v173, s42, -v121
	v_fma_f32 v100, v237, s42, -v121
	v_fma_f32 v102, v171, s42, -v121
	v_exp_f32_e32 v96, v96
	v_fma_f32 v97, v178, s42, -v121
	v_exp_f32_e32 v98, v98
	v_fma_f32 v99, v179, s42, -v121
	v_exp_f32_e32 v100, v100
	v_fma_f32 v101, v180, s42, -v121
	v_exp_f32_e32 v102, v102
	v_fma_f32 v103, v181, s42, -v121
	global_load_dwordx4 v[64:67], v[64:65], off nt
	v_exp_f32_e32 v97, v97
	v_exp_f32_e32 v99, v99
	v_exp_f32_e32 v101, v101
	v_exp_f32_e32 v103, v103
	v_pk_mul_f32 v[140:141], v[112:113], v[170:171] op_sel_hi:[1,0]
	v_pk_mul_f32 v[112:113], v[116:117], v[170:171] op_sel_hi:[1,0]
	v_add_f32_e32 v116, v96, v98
	v_add_f32_e32 v117, v100, v102
	v_pk_mul_f32 v[142:143], v[114:115], v[170:171] op_sel_hi:[1,0]
	v_pk_mul_f32 v[114:115], v[118:119], v[170:171] op_sel_hi:[1,0]
	v_add_f32_e32 v116, v116, v117
	v_add_f32_e32 v117, v97, v99
	v_add_f32_e32 v118, v101, v103
	v_add_f32_e32 v117, v117, v118
	v_pk_mul_f32 v[146:147], v[110:111], v[170:171] op_sel_hi:[1,0]
	v_pk_mul_f32 v[110:111], v[122:123], v[170:171] op_sel_hi:[1,0]
	v_add_f32_e32 v122, v116, v117
	v_cvt_pk_bf16_f32 v116, v96, v98
	v_cvt_pk_bf16_f32 v117, v100, v102
	v_fma_f32 v100, v174, s42, -v121
	v_cvt_pk_bf16_f32 v118, v97, v99
	v_cvt_pk_bf16_f32 v119, v101, v103
	v_exp_f32_e32 v101, v100
	v_fma_f32 v100, v188, s42, -v121
	v_fma_f32 v96, v176, s42, -v121
	v_fma_f32 v98, v177, s42, -v121
	v_exp_f32_e32 v103, v100
	v_fma_f32 v100, v175, s42, -v121
	v_exp_f32_e32 v96, v96
	v_fma_f32 v97, v186, s42, -v121
	global_load_dwordx4 v[68:71], v[68:69], off nt
	v_exp_f32_e32 v98, v98
	v_fma_f32 v99, v187, s42, -v121
	v_exp_f32_e32 v102, v100
	v_fma_f32 v100, v189, s42, -v121
	v_exp_f32_e32 v97, v97
	v_exp_f32_e32 v99, v99
	v_exp_f32_e32 v123, v100
	v_pk_mul_f32 v[136:137], v[104:105], v[170:171] op_sel_hi:[1,0]
	v_pk_mul_f32 v[104:105], v[124:125], v[170:171] op_sel_hi:[1,0]
	v_add_f32_e32 v100, v96, v98
	v_add_f32_e32 v124, v101, v102
	v_add_f32_e32 v100, v100, v124
	v_add_f32_e32 v124, v97, v99
	v_add_f32_e32 v125, v103, v123
	v_add_f32_e32 v124, v124, v125
	v_fmac_f32_e32 v122, v236, v170
	v_add_f32_e32 v100, v100, v124
	v_add_f32_e32 v122, v100, v122
	v_cvt_pk_bf16_f32 v100, v96, v98
	v_cvt_pk_bf16_f32 v101, v101, v102
	v_cvt_pk_bf16_f32 v102, v97, v99
	v_fma_f32 v97, v194, s42, -v121
	v_cvt_pk_bf16_f32 v103, v103, v123
	v_fma_f32 v96, v184, s42, -v121
	v_exp_f32_e32 v98, v97
	v_fma_f32 v97, v185, s42, -v121
	v_fma_f32 v123, v182, s42, -v121
	v_fma_f32 v125, v183, s42, -v121
	v_pk_mul_f32 v[138:139], v[106:107], v[170:171] op_sel_hi:[1,0]
	v_pk_mul_f32 v[106:107], v[126:127], v[170:171] op_sel_hi:[1,0]
	global_load_dwordx4 v[72:75], v[74:75], off nt
	v_exp_f32_e32 v96, v96
	v_exp_f32_e32 v97, v97
	v_fma_f32 v99, v195, s42, -v121
	v_exp_f32_e32 v123, v123
	v_fma_f32 v124, v196, s42, -v121
	v_exp_f32_e32 v125, v125
	v_fma_f32 v126, v197, s42, -v121
	v_exp_f32_e32 v99, v99
	v_exp_f32_e32 v124, v124
	v_exp_f32_e32 v126, v126
	v_add_f32_e32 v127, v96, v97
	v_add_f32_e32 v167, v123, v125
	v_add_f32_e32 v127, v127, v167
	v_add_f32_e32 v167, v98, v99
	v_add_f32_e32 v168, v124, v126
	v_add_f32_e32 v167, v167, v168
	v_add_f32_e32 v127, v127, v167
	v_cvt_pk_bf16_f32 v96, v96, v97
	v_cvt_pk_bf16_f32 v97, v123, v125
	v_fma_f32 v125, v199, s42, -v121
	v_add_f32_e32 v167, v127, v122
	v_cvt_pk_bf16_f32 v98, v98, v99
	v_cvt_pk_bf16_f32 v99, v124, v126
	v_fma_f32 v122, v192, s42, -v121
	v_fma_f32 v124, v193, s42, -v121
	v_exp_f32_e32 v126, v125
	v_fma_f32 v125, v190, s42, -v121
	v_fma_f32 v127, v191, s42, -v121
	v_exp_f32_e32 v122, v122
	v_fma_f32 v123, v198, s42, -v121
	global_load_dwordx4 v[76:79], v[76:77], off nt
	v_exp_f32_e32 v124, v124
	v_exp_f32_e32 v125, v125
	v_sub_f32_e32 v120, v120, v121
	v_exp_f32_e32 v127, v127
	v_fma_f32 v121, v201, s42, -v121
	v_exp_f32_e32 v123, v123
	v_exp_f32_e32 v120, v120
	v_exp_f32_e32 v121, v121
	v_add_u32_e32 v178, s67, v225
	v_add_f32_e32 v168, v122, v124
	v_add_f32_e32 v170, v125, v127
	v_add3_u32 v179, v178, v224, v221
	v_add_f32_e32 v168, v168, v170
	v_add_f32_e32 v170, v123, v126
	v_add_f32_e32 v171, v120, v121
	v_cvt_pk_bf16_f32 v124, v122, v124
	v_cvt_pk_bf16_f32 v125, v125, v127
	v_cvt_pk_bf16_f32 v126, v123, v126
	v_cvt_pk_bf16_f32 v127, v120, v121
	ds_read_b64_tr_b16 v[120:121], v179 offset:34816
	ds_read_b64_tr_b16 v[122:123], v179 offset:38912
	v_add_f32_e32 v170, v170, v171
	v_add_f32_e32 v168, v168, v170
	s_waitcnt lgkmcnt(0)
	v_mfma_f32_16x16x32_bf16 v[170:173], v[120:123], v[116:119], v[132:135]
	v_add3_u32 v180, v178, v227, v221
	s_nop 1
	v_add3_u32 v133, v178, v226, v221
	ds_read_b64_tr_b16 v[120:121], v133 offset:34816
	ds_read_b64_tr_b16 v[122:123], v133 offset:38912
	s_waitcnt lgkmcnt(0)
	v_mfma_f32_16x16x32_bf16 v[128:131], v[120:123], v[116:119], v[128:131]
	ds_read_b64_tr_b16 v[120:121], v180 offset:34816
	ds_read_b64_tr_b16 v[122:123], v180 offset:38912
	v_add3_u32 v181, v178, v228, v221
	v_add3_u32 v182, v178, v229, v221
	s_waitcnt lgkmcnt(0)
; #define LAS __attribute__((address_space(3)))
; __device__ __forceinline__ bf16x8 tr_frag(LAS unsigned char* vimg, int rbase, int c, int lane) {
;     const unsigned fq = lane >> 4, q = (lane & 15) >> 2, p = lane & 3;
;     const unsigned r0 = rbase + 4 * fq + q, r1 = r0 + 16;
;     const s16x4 t0 = __builtin_amdgcn_ds_read_tr16_b64_v4i16((LAS s16x4*)(vimg + offb(r0, 2 * c + (p >> 1)) + 8 * (p & 1)));
;     const s16x4 t1 = __builtin_amdgcn_ds_read_tr16_b64_v4i16((LAS s16x4*)(vimg + offb(r1, 2 * c + (p >> 1)) + 8 * (p & 1)));
;     return __builtin_shufflevector(t0, t1, 0, 1, 2, 3, 4, 5, 6, 7);
; __device__ __forceinline__ void attn_stream(LAS unsigned char* lds, const MixArgs& A, ConvJob& J, int vcu, int G, int tid, int wid, int lane) {
;     ...
;         for (int ks = 0; ks < 4; ++ks)
; #pragma unroll
;             for (int c = 0; c < 8; ++c) { const bf16x8 a = tr_frag(vbase, 32 * ks, c, lane);
;                 oacc[c] = __builtin_amdgcn_mfma_f32_16x16x32_bf16(a, pf[ks], oacc[c], 0, 0, 0); }
	v_mfma_f32_16x16x32_bf16 v[134:137], v[120:123], v[116:119], v[136:139]
	ds_read_b64_tr_b16 v[120:121], v181 offset:34816
	ds_read_b64_tr_b16 v[122:123], v181 offset:38912
	v_add3_u32 v183, v178, v230, v221
	v_add3_u32 v132, v178, v232, v221
	s_waitcnt lgkmcnt(0)
	v_mfma_f32_16x16x32_bf16 v[144:147], v[120:123], v[116:119], v[144:147]
	ds_read_b64_tr_b16 v[120:121], v182 offset:34816
	ds_read_b64_tr_b16 v[122:123], v182 offset:38912
	v_add_f32_e32 v236, v168, v167
	s_waitcnt lgkmcnt(0)
	v_mfma_f32_16x16x32_bf16 v[138:141], v[120:123], v[116:119], v[140:143]
	ds_read_b64_tr_b16 v[120:121], v183 offset:34816
	ds_read_b64_tr_b16 v[122:123], v183 offset:38912
	s_waitcnt lgkmcnt(0)
	v_mfma_f32_16x16x32_bf16 v[112:115], v[120:123], v[116:119], v[112:115]
	v_add3_u32 v120, v178, v231, v221
	ds_read_b64_tr_b16 v[174:175], v120 offset:34816
	ds_read_b64_tr_b16 v[176:177], v120 offset:38912
	s_waitcnt lgkmcnt(0)
	v_mfma_f32_16x16x32_bf16 v[108:111], v[174:177], v[116:119], v[108:111]
	ds_read_b64_tr_b16 v[174:175], v132 offset:34816
	ds_read_b64_tr_b16 v[176:177], v132 offset:38912
	s_waitcnt lgkmcnt(0)
	v_mfma_f32_16x16x32_bf16 v[104:107], v[174:177], v[116:119], v[104:107]
	ds_read_b64_tr_b16 v[116:117], v179 offset:43008
	ds_read_b64_tr_b16 v[118:119], v179 offset:47104
	s_waitcnt lgkmcnt(0)
	v_mfma_f32_16x16x32_bf16 v[116:119], v[116:119], v[100:103], v[170:173]
	s_nop 2
	ds_read_b64_tr_b16 v[170:171], v133 offset:43008
	ds_read_b64_tr_b16 v[172:173], v133 offset:47104
	s_waitcnt lgkmcnt(0)
	v_mfma_f32_16x16x32_bf16 v[128:131], v[170:173], v[100:103], v[128:131]
	ds_read_b64_tr_b16 v[170:171], v180 offset:43008
	ds_read_b64_tr_b16 v[172:173], v180 offset:47104
	s_waitcnt lgkmcnt(0)
	v_mfma_f32_16x16x32_bf16 v[134:137], v[170:173], v[100:103], v[134:137]
	ds_read_b64_tr_b16 v[170:171], v181 offset:43008
	ds_read_b64_tr_b16 v[172:173], v181 offset:47104
	s_waitcnt lgkmcnt(0)
	v_mfma_f32_16x16x32_bf16 v[142:145], v[170:173], v[100:103], v[144:147]
	ds_read_b64_tr_b16 v[170:171], v182 offset:43008
	ds_read_b64_tr_b16 v[172:173], v182 offset:47104
	s_waitcnt lgkmcnt(0)
	v_mfma_f32_16x16x32_bf16 v[138:141], v[170:173], v[100:103], v[138:141]
	ds_read_b64_tr_b16 v[170:171], v183 offset:43008
	ds_read_b64_tr_b16 v[172:173], v183 offset:47104
	s_waitcnt lgkmcnt(0)
	v_mfma_f32_16x16x32_bf16 v[112:115], v[170:173], v[100:103], v[112:115]
	ds_read_b64_tr_b16 v[170:171], v120 offset:43008
	ds_read_b64_tr_b16 v[172:173], v120 offset:47104
	s_waitcnt lgkmcnt(0)
	v_mfma_f32_16x16x32_bf16 v[108:111], v[170:173], v[100:103], v[108:111]
	ds_read_b64_tr_b16 v[170:171], v132 offset:43008
	ds_read_b64_tr_b16 v[172:173], v132 offset:47104
	s_waitcnt lgkmcnt(0)
	v_mfma_f32_16x16x32_bf16 v[100:103], v[170:173], v[100:103], v[104:107]
	s_nop 2
	ds_read_b64_tr_b16 v[104:105], v179 offset:51200
	ds_read_b64_tr_b16 v[106:107], v179 offset:55296
	s_waitcnt lgkmcnt(0)
	v_mfma_f32_16x16x32_bf16 v[104:107], v[104:107], v[96:99], v[116:119]
	s_nop 2
	ds_read_b64_tr_b16 v[116:117], v133 offset:51200
	ds_read_b64_tr_b16 v[118:119], v133 offset:55296
	s_waitcnt lgkmcnt(0)
	v_mfma_f32_16x16x32_bf16 v[116:119], v[116:119], v[96:99], v[128:131]
	s_nop 2
	ds_read_b64_tr_b16 v[128:129], v180 offset:51200
	ds_read_b64_tr_b16 v[130:131], v180 offset:55296
	s_waitcnt lgkmcnt(0)
	v_mfma_f32_16x16x32_bf16 v[134:137], v[128:131], v[96:99], v[134:137]
	ds_read_b64_tr_b16 v[128:129], v181 offset:51200
	ds_read_b64_tr_b16 v[130:131], v181 offset:55296
	s_waitcnt lgkmcnt(0)
	v_mfma_f32_16x16x32_bf16 v[142:145], v[128:131], v[96:99], v[142:145]
	ds_read_b64_tr_b16 v[128:129], v182 offset:51200
	ds_read_b64_tr_b16 v[130:131], v182 offset:55296
	s_waitcnt lgkmcnt(0)
	v_mfma_f32_16x16x32_bf16 v[138:141], v[128:131], v[96:99], v[138:141]
	ds_read_b64_tr_b16 v[128:129], v183 offset:51200
	ds_read_b64_tr_b16 v[130:131], v183 offset:55296
	s_waitcnt lgkmcnt(0)
	v_mfma_f32_16x16x32_bf16 v[170:173], v[128:131], v[96:99], v[112:115]
	s_nop 2
	ds_read_b64_tr_b16 v[112:113], v120 offset:51200
	ds_read_b64_tr_b16 v[114:115], v120 offset:55296
	s_waitcnt lgkmcnt(0)
	v_mfma_f32_16x16x32_bf16 v[174:177], v[112:115], v[96:99], v[108:111]
	s_nop 2
	ds_read_b64_tr_b16 v[108:109], v132 offset:51200
	ds_read_b64_tr_b16 v[110:111], v132 offset:55296
	s_waitcnt lgkmcnt(0)
	v_mfma_f32_16x16x32_bf16 v[128:131], v[108:111], v[96:99], v[100:103]
	ds_read_b64_tr_b16 v[96:97], v179 offset:59392
	ds_read_b64_tr_b16 v[98:99], v179 offset:63488
	s_nop 0
	ds_read_b64_tr_b16 v[100:101], v133 offset:59392
	ds_read_b64_tr_b16 v[102:103], v133 offset:63488
	s_waitcnt lgkmcnt(2)
	v_mfma_f32_16x16x32_bf16 v[96:99], v[96:99], v[124:127], v[104:107]
	s_nop 2
	ds_read_b64_tr_b16 v[104:105], v180 offset:59392
	ds_read_b64_tr_b16 v[106:107], v180 offset:63488
	ds_read_b64_tr_b16 v[108:109], v181 offset:59392
	ds_read_b64_tr_b16 v[110:111], v181 offset:63488
	ds_read_b64_tr_b16 v[112:113], v182 offset:59392
	ds_read_b64_tr_b16 v[114:115], v182 offset:63488
	s_waitcnt lgkmcnt(6)
	v_mfma_f32_16x16x32_bf16 v[100:103], v[100:103], v[124:127], v[116:119]
	s_nop 2
	ds_read_b64_tr_b16 v[116:117], v183 offset:59392
	ds_read_b64_tr_b16 v[118:119], v183 offset:63488
	s_waitcnt lgkmcnt(6)
	v_mfma_f32_16x16x32_bf16 v[104:107], v[104:107], v[124:127], v[134:137]
	s_nop 2
	ds_read_b64_tr_b16 v[134:135], v120 offset:59392
	ds_read_b64_tr_b16 v[136:137], v120 offset:63488
	s_waitcnt lgkmcnt(0)
	v_mfma_f32_16x16x32_bf16 v[120:123], v[134:137], v[124:127], v[174:177]
	ds_read_b64_tr_b16 v[134:135], v132 offset:59392
	ds_read_b64_tr_b16 v[136:137], v132 offset:63488
	v_mfma_f32_16x16x32_bf16 v[108:111], v[108:111], v[124:127], v[142:145]
	v_mfma_f32_16x16x32_bf16 v[112:115], v[112:115], v[124:127], v[138:141]
	v_mfma_f32_16x16x32_bf16 v[116:119], v[116:119], v[124:127], v[170:173]
	s_waitcnt lgkmcnt(0)
	v_mfma_f32_16x16x32_bf16 v[124:127], v[134:137], v[124:127], v[128:131]
	s_cbranch_scc0 .LBB0_172
	s_andn2_b64 vcc, exec, s[10:11]
	s_cbranch_vccz .LBB0_175

; #define GM_LOADV(bb_, hh_) do { const size_t t_ = (size_t)(bb_) * 128 + skey; const bf16_t* vp_ = A.Z + t_ * INW + O_G + (hh_) * 128 + 8 * spart; \
;         _Pragma("unroll") for (int i = 0; i < 4; ++i) vr[i] = *(const u32x4*)(vp_ + 32 * i); \
;         pa = *(const f32x4*)(A.VSS + t_ * 32 + 8 * spart); pb = *(const f32x4*)(A.VSS + t_ * 32 + 8 * spart + 4); } while (0)
; __device__ __forceinline__ void gmlp_stream(LAS unsigned char* lds, const MixArgs& A, ConvJob& J, int vcu, int G, int tid, int wid, int lane) {
;     ...
;     int u = vcu, hh = u & 15, bb = u >> 4;
;     u32x4 vr[4]; f32x4 pa, pb;
;     ...
;     GM_LOADV(bb, hh);
;     u32x2 uu[8];
;     { const bf16_t* up0 = A.Z + ((size_t)bb * 128 + trow) * INW + O_U + hh * 128 + 4 * fq;
; #pragma unroll
;       for (int c = 0; c < 8; ++c) uu[c] = *(const u32x2*)(up0 + 16 * c); }
;     __syncthreads();
;     GM_WRITEV(0, hh);
.LBB0_180:
	s_andn2_b64 vcc, exec, s[50:51]
	s_waitcnt vmcnt(0)
	v_and_b32_e32 v72, 56, v202
	s_cbranch_vccnz .LBB0_197
	s_ashr_i32 s48, s78, 4
	s_ashr_i32 s49, s48, 31
	v_mov_b32_e32 v153, 0
	s_lshl_b64 s[0:1], s[48:49], 7
	v_mov_b32_e32 v149, v153
	s_waitcnt lgkmcnt(0)
	v_lshl_add_u64 v[0:1], s[0:1], 0, v[148:149]
	s_movk_i32 s56, 0x3800
	v_mov_b64_e32 v[12:13], s[18:19]
	s_and_b32 s42, s78, 15
	v_mad_u64_u32 v[2:3], s[4:5], v0, s56, v[12:13]
	s_mov_b32 s7, 0
	s_mov_b32 s99, -1
	v_mad_i32_i24 v3, v1, s56, v3
	s_lshl_b32 s6, s42, 8
	v_lshl_add_u64 v[2:3], v[2:3], 0, s[6:7]
	v_lshlrev_b64 v[0:1], 7, v[0:1]
	v_lshl_add_u64 v[14:15], v[2:3], 0, v[152:153]
	v_lshl_add_u64 v[0:1], s[40:41], 0, v[0:1]
	v_lshlrev_b32_e32 v152, 5, v159
	v_lshl_add_u64 v[0:1], v[0:1], 0, v[152:153]
	global_load_dwordx4 v[4:7], v[0:1], off
	s_nop 0
	global_load_dwordx4 v[0:3], v[0:1], off offset:16
	v_mov_b32_e32 v151, v153
	v_lshl_add_u64 v[18:19], s[0:1], 0, v[150:151]
	s_movk_i32 s57, 0x2000
	v_mad_u64_u32 v[12:13], s[0:1], v18, s56, v[12:13]
	v_and_b32_e32 v74, 12, v148
	v_add_co_u32_e32 v8, vcc, s57, v14
	v_mad_i32_i24 v13, v19, s56, v13
	v_lshlrev_b32_e32 v16, 1, v74
	v_mov_b32_e32 v17, v153
	v_addc_co_u32_e32 v9, vcc, 0, v15, vcc
	v_lshl_add_u64 v[12:13], v[12:13], 0, s[6:7]
	s_movk_i32 s58, 0x1000
	s_lshl_b32 s4, s42, 9
	global_load_dwordx4 v[8:11], v[8:9], off offset:2048
	v_lshl_add_u64 v[12:13], v[12:13], 0, v[16:17]
	s_mov_b64 s[8:9], 0x2800
	s_mov_b64 s[10:11], 0x1800
	s_add_u32 s4, s12, s4
	v_add_co_u32_e32 v26, vcc, s58, v12
	s_addc_u32 s5, s13, 0
	v_lshl_add_u64 v[20:21], v[14:15], 0, s[8:9]
	v_lshl_add_u64 v[24:25], v[12:13], 0, s[10:11]
	v_addc_co_u32_e32 v27, vcc, 0, v13, vcc
	global_load_dwordx4 v[12:15], v[20:21], off offset:64
	global_load_dwordx4 v[16:19], v[20:21], off offset:128
	s_nop 0
	global_load_dwordx4 v[20:23], v[20:21], off offset:192
	s_nop 0
	global_load_dwordx2 v[114:115], v[24:25], off offset:32
	global_load_dwordx2 v[112:113], v[24:25], off offset:64
	global_load_dwordx2 v[110:111], v[24:25], off offset:96
	global_load_dwordx2 v[108:109], v[24:25], off offset:128
	global_load_dwordx2 v[116:117], v[26:27], off offset:2048
	global_load_dwordx2 v[106:107], v[24:25], off offset:160
	global_load_dwordx2 v[104:105], v[24:25], off offset:192
	global_load_dwordx2 v[102:103], v[24:25], off offset:224
	s_barrier
	global_load_dwordx4 v[24:27], v152, s[4:5]
	global_load_dwordx4 v[28:31], v152, s[4:5] offset:16
	v_mbcnt_lo_u32_b32 v32, -1, 0
	v_mbcnt_hi_u32_b32 v41, -1, v32
	v_and_b32_e32 v33, 64, v41
	v_xor_b32_e32 v32, 1, v41
	v_add_u32_e32 v71, 64, v33
	v_cmp_lt_i32_e32 vcc, v32, v71
	v_mov_b32_e32 v87, 0x358637bd
	s_mov_b32 s59, 0xf800000
	v_cndmask_b32_e32 v32, v41, v32, vcc
	v_lshlrev_b32_e32 v73, 2, v32
	v_mov_b32_e32 v120, 0x260
	v_and_b32_e32 v96, 12, v202
	v_bfe_u32 v97, v202, 4, 2
	v_lshlrev_b32_e32 v76, 1, v154
	s_mov_b32 s60, -1
	s_movk_i32 s61, 0x7f
	s_mov_b64 s[44:45], 0x1000
	s_movk_i32 s62, 0x4040
	v_mov_b32_e32 v125, 0
	s_mov_b32 s63, 0
	v_mov_b32_e32 v56, v153
	v_mov_b32_e32 v57, v153
	v_mov_b32_e32 v58, v153
	v_mov_b32_e32 v59, v153
	v_mov_b32_e32 v60, v153
	v_mov_b32_e32 v61, v153
	v_mov_b32_e32 v62, v153
	v_mov_b32_e32 v63, v153
	v_mov_b32_e32 v64, v153
	v_mov_b32_e32 v65, v153
	v_mov_b32_e32 v66, v153
	v_mov_b32_e32 v67, v153
	v_mov_b32_e32 v68, v153
	v_mov_b32_e32 v69, v153
	v_mov_b32_e32 v70, v153
	s_waitcnt vmcnt(15)
	v_mov_b32_e32 v32, v4
	s_waitcnt vmcnt(14)
	v_mov_b32_e32 v33, v0
	v_mov_b32_e32 v34, v5
	v_mov_b32_e32 v35, v1
	v_mov_b32_e32 v36, v6
	v_mov_b32_e32 v37, v2
	v_mov_b32_e32 v38, v7
	v_mov_b32_e32 v39, v3
	v_pk_add_f32 v[32:33], v[32:33], v[34:35]
	v_pk_add_f32 v[34:35], v[36:37], v[38:39]
	s_waitcnt vmcnt(12)
	v_lshlrev_b32_e32 v40, 16, v13
	v_pk_add_f32 v[32:33], v[32:33], v[34:35]
	v_xor_b32_e32 v34, 2, v41
	v_add_f32_e32 v32, v32, v33
	ds_bpermute_b32 v33, v73, v32
	v_cmp_lt_i32_e32 vcc, v34, v71
	v_and_b32_e32 v42, 0xffff0000, v13
	v_lshlrev_b32_e32 v43, 16, v14
	v_cndmask_b32_e32 v34, v41, v34, vcc
	v_lshlrev_b32_e32 v75, 2, v34
	s_waitcnt lgkmcnt(0)
	v_add_f32_e32 v32, v32, v33
	ds_bpermute_b32 v33, v75, v32
	v_lshlrev_b32_e32 v34, 16, v8
	v_and_b32_e32 v44, 0xffff0000, v14
	v_lshlrev_b32_e32 v45, 16, v15
	v_and_b32_e32 v46, 0xffff0000, v15
	s_waitcnt lgkmcnt(0)
	v_add_f32_e32 v32, v32, v33
	v_fmamk_f32 v32, v32, 0x3a000000, v87
	v_mul_f32_e32 v33, 0x4f800000, v32
	v_cmp_gt_f32_e32 vcc, s59, v32
	s_waitcnt vmcnt(11)
	v_lshlrev_b32_e32 v50, 16, v17
	v_and_b32_e32 v51, 0xffff0000, v17
	v_cndmask_b32_e32 v32, v32, v33, vcc
	v_sqrt_f32_e32 v33, v32
	v_lshlrev_b32_e32 v52, 16, v18
	v_and_b32_e32 v53, 0xffff0000, v18
	v_lshlrev_b32_e32 v54, 16, v19
	v_add_u32_e32 v35, -1, v33
	v_add_u32_e32 v36, 1, v33
	v_fma_f32 v37, -v35, v33, v32
	v_fma_f32 v38, -v36, v33, v32
	v_cmp_ge_f32_e64 s[0:1], 0, v37
	v_and_b32_e32 v55, 0xffff0000, v19
	s_nop 0
	v_cndmask_b32_e64 v33, v33, v35, s[0:1]
	v_cmp_lt_f32_e64 s[0:1], 0, v38
	s_nop 1
	v_cndmask_b32_e64 v33, v33, v36, s[0:1]
	v_mul_f32_e32 v35, 0x37800000, v33
	v_cndmask_b32_e32 v33, v33, v35, vcc
	v_cmp_class_f32_e32 vcc, v32, v120
	v_and_b32_e32 v36, 0xffff0000, v8
	s_nop 0
	v_cndmask_b32_e32 v32, v33, v32, vcc
	v_div_scale_f32 v33, s[0:1], v32, v32, 1.0
	v_rcp_f32_e32 v35, v33
	v_div_scale_f32 v37, vcc, 1.0, v32, 1.0
	v_cmp_gt_u32_e64 s[0:1], 16, v155
	v_fma_f32 v38, -v33, v35, 1.0
	v_fmac_f32_e32 v35, v38, v35
	v_mul_f32_e32 v38, v37, v35
	v_fma_f32 v39, -v33, v38, v37
	v_fmac_f32_e32 v38, v39, v35
	v_fma_f32 v33, -v33, v38, v37
	v_div_fmas_f32 v33, v33, v35, v38
	v_div_fixup_f32 v77, v33, v32, 1.0
	v_mul_f32_e32 v32, v77, v34
	s_waitcnt vmcnt(1)
; #define GM_LOADV(bb_, hh_) do { const size_t t_ = (size_t)(bb_) * 128 + skey; const bf16_t* vp_ = A.Z + t_ * INW + O_G + (hh_) * 128 + 8 * spart; \
;         _Pragma("unroll") for (int i = 0; i < 4; ++i) vr[i] = *(const u32x4*)(vp_ + 32 * i); \
;         pa = *(const f32x4*)(A.VSS + t_ * 32 + 8 * spart); pb = *(const f32x4*)(A.VSS + t_ * 32 + 8 * spart + 4); } while (0)
; __device__ __forceinline__ void gmlp_stream(LAS unsigned char* lds, const MixArgs& A, ConvJob& J, int vcu, int G, int tid, int wid, int lane) {
;     ...
;     GM_LOADV(bb, hh);
;     u32x2 uu[8];
;     { const bf16_t* up0 = A.Z + ((size_t)bb * 128 + trow) * INW + O_U + hh * 128 + 4 * fq;
; #pragma unroll
;       for (int c = 0; c < 8; ++c) uu[c] = *(const u32x2*)(up0 + 16 * c); }
;     __syncthreads();
;     GM_WRITEV(0, hh);
;     int buf = 0, w_head = -1; bf16x8 wf[4]; float bsv = 0.f;
	v_mul_f32_e32 v24, v24, v32
	v_mul_f32_e32 v32, v77, v36
	v_mul_f32_e32 v25, v25, v32
	v_cvt_pk_bf16_f32 v24, v24, v25
	v_lshlrev_b32_e32 v25, 16, v9
	v_mul_f32_e32 v25, v77, v25
	v_mul_f32_e32 v25, v26, v25
	v_and_b32_e32 v26, 0xffff0000, v9
	v_mul_f32_e32 v26, v77, v26
	v_mul_f32_e32 v26, v27, v26
	v_cvt_pk_bf16_f32 v25, v25, v26
	v_lshlrev_b32_e32 v26, 16, v10
	v_and_b32_e32 v27, 0xffff0000, v10
	v_mul_f32_e32 v26, v77, v26
	v_mul_f32_e32 v27, v77, v27
	s_waitcnt vmcnt(0)
	v_mul_f32_e32 v26, v28, v26
	v_mul_f32_e32 v27, v29, v27
	v_cvt_pk_bf16_f32 v26, v26, v27
	v_lshlrev_b32_e32 v27, 16, v11
	v_and_b32_e32 v28, 0xffff0000, v11
	v_mul_f32_e32 v27, v77, v27
	v_mul_f32_e32 v28, v77, v28
	v_mul_f32_e32 v27, v30, v27
	v_mul_f32_e32 v28, v31, v28
	v_cvt_pk_bf16_f32 v27, v27, v28
	global_load_dwordx4 v[28:31], v152, s[4:5] offset:128
	global_load_dwordx4 v[32:35], v152, s[4:5] offset:144
	v_lshlrev_b32_e32 v38, 8, v148
	v_bitop3_b32 v36, v97, v159, v96 bitop3:0x36
	v_add_u32_e32 v121, 0, v38
	v_lshlrev_b32_e32 v122, 4, v36
	v_lshlrev_b32_e32 v37, 16, v12
	v_and_b32_e32 v39, 0xffff0000, v12
	v_add_u32_e32 v36, v121, v122
	v_mul_f32_e32 v37, v77, v37
	v_mul_f32_e32 v39, v77, v39
	v_mul_f32_e32 v40, v77, v40
	v_mul_f32_e32 v42, v77, v42
	v_mul_f32_e32 v43, v77, v43
	v_mul_f32_e32 v44, v77, v44
	v_mul_f32_e32 v45, v77, v45
	v_mul_f32_e32 v46, v77, v46
	ds_write_b128 v36, v[24:27] offset:34816
	v_mul_f32_e32 v50, v77, v50
	v_mul_f32_e32 v51, v77, v51
	v_mul_f32_e32 v52, v77, v52
	v_mul_f32_e32 v53, v77, v53
	v_mul_f32_e32 v54, v77, v54
	v_mul_f32_e32 v55, v77, v55
	s_waitcnt vmcnt(1)
	v_mul_f32_e32 v24, v37, v28
	v_mul_f32_e32 v25, v39, v29
	v_mul_f32_e32 v26, v40, v30
	v_mul_f32_e32 v27, v42, v31
	s_waitcnt vmcnt(0)
	v_mul_f32_e32 v28, v43, v32
	v_mul_f32_e32 v29, v44, v33
	v_mul_f32_e32 v30, v45, v34
	v_mul_f32_e32 v31, v46, v35
	v_cvt_pk_bf16_f32 v34, v24, v25
	v_cvt_pk_bf16_f32 v35, v26, v27
	v_cvt_pk_bf16_f32 v36, v28, v29
	v_cvt_pk_bf16_f32 v37, v30, v31
	global_load_dwordx4 v[42:45], v152, s[4:5] offset:256
	global_load_dwordx4 v[46:49], v152, s[4:5] offset:272
	v_or_b32_e32 v25, 4, v159
	v_lshlrev_b32_e32 v31, 3, v202
	v_bitop3_b32 v25, v97, v25, v96 bitop3:0x36
	v_and_b32_e32 v123, 8, v31
	v_and_b32_e32 v31, 0xf00, v38
	v_lshlrev_b32_e32 v124, 4, v25
	v_lshlrev_b32_e32 v38, 16, v16
	v_and_b32_e32 v39, 0xffff0000, v16
	v_add_u32_e32 v25, v121, v124
	v_mul_f32_e32 v38, v77, v38
	v_mul_f32_e32 v39, v77, v39
	ds_write_b128 v25, v[34:37] offset:34816
	v_or_b32_e32 v26, 8, v159
	v_lshlrev_b32_e32 v29, 2, v202
	v_bfe_u32 v30, v202, 1, 1
	v_bitop3_b32 v33, v97, v26, v96 bitop3:0x36
	v_and_b32_e32 v86, 28, v29
	v_bitop3_b32 v29, v97, v30, v96 bitop3:0x36
	v_or_b32_e32 v99, 2, v30
	v_lshlrev_b32_e32 v126, 4, v33
	v_xor_b32_e32 v33, 32, v41
	v_or_b32_e32 v27, 12, v159
	v_or_b32_e32 v100, 4, v30
	v_or_b32_e32 v101, 6, v30
	v_or_b32_e32 v118, 8, v30
	v_or_b32_e32 v119, 10, v30
	v_or_b32_e32 v129, 12, v30
	v_or_b32_e32 v30, 14, v30
	v_lshlrev_b32_e32 v128, 4, v29
	v_bitop3_b32 v29, v97, v99, v96 bitop3:0x36
	v_bitop3_b32 v98, v97, v27, v96 bitop3:0x36
	v_bitop3_b32 v30, v97, v30, v96 bitop3:0x36
	v_lshlrev_b32_e32 v130, 4, v29
	v_lshlrev_b32_e32 v26, 2, v74
	v_mov_b32_e32 v27, v153
	v_lshlrev_b32_e32 v127, 4, v98
	v_bitop3_b32 v98, v97, v129, v96 bitop3:0x36
	v_add_u32_e32 v129, 0, v31
	v_lshlrev_b32_e32 v136, 4, v30
	v_lshlrev_b32_e32 v30, 16, v21
	v_and_b32_e32 v31, 0xffff0000, v21
	v_mul_f32_e32 v30, v77, v30
	v_mul_f32_e32 v31, v77, v31
	v_lshlrev_b32_e32 v135, 4, v98
	v_lshl_add_u64 v[98:99], s[40:41], 0, v[152:153]
	s_waitcnt vmcnt(1)
	v_mul_f32_e32 v25, v38, v42
	v_mul_f32_e32 v34, v39, v43
	v_mul_f32_e32 v35, v50, v44
	v_mul_f32_e32 v36, v51, v45
	s_waitcnt vmcnt(0)
	v_mul_f32_e32 v37, v52, v46
	v_mul_f32_e32 v38, v53, v47
	v_mul_f32_e32 v39, v54, v48
	v_mul_f32_e32 v42, v55, v49
	v_cvt_pk_bf16_f32 v140, v25, v34
	v_cvt_pk_bf16_f32 v141, v35, v36
	v_cvt_pk_bf16_f32 v142, v37, v38
	v_cvt_pk_bf16_f32 v143, v39, v42
	global_load_dwordx4 v[144:147], v152, s[4:5] offset:400
	global_load_dwordx4 v[154:157], v152, s[4:5] offset:384
	v_xor_b32_e32 v25, 16, v41
	v_cmp_lt_i32_e32 vcc, v25, v71
	v_bitop3_b32 v34, v97, v100, v96 bitop3:0x36
	v_bitop3_b32 v35, v97, v101, v96 bitop3:0x36
	v_cndmask_b32_e32 v25, v41, v25, vcc
	v_cmp_lt_i32_e32 vcc, v33, v71
	v_lshlrev_b32_e32 v131, 4, v34
	v_lshlrev_b32_e32 v132, 4, v35
	v_cndmask_b32_e32 v29, v41, v33, vcc
	v_lshlrev_b32_e32 v137, 2, v25
	v_lshlrev_b32_e32 v138, 2, v29
	v_lshlrev_b32_e32 v25, 16, v20
	v_and_b32_e32 v29, 0xffff0000, v20
	v_lshlrev_b32_e32 v33, 16, v22
	v_and_b32_e32 v34, 0xffff0000, v22
	v_lshlrev_b32_e32 v35, 16, v23
	v_and_b32_e32 v41, 0xffff0000, v23
	v_bitop3_b32 v42, v97, v118, v96 bitop3:0x36
	v_bitop3_b32 v43, v97, v119, v96 bitop3:0x36
	v_lshl_add_u64 v[96:97], s[14:15], 0, v[26:27]
	v_add_u32_e32 v26, v121, v126
	v_mul_f32_e32 v25, v77, v25
	v_mul_f32_e32 v29, v77, v29
	v_mul_f32_e32 v33, v77, v33
	v_mul_f32_e32 v34, v77, v34
	v_mul_f32_e32 v35, v77, v35
	v_mul_f32_e32 v41, v77, v41
	v_mov_b32_e32 v36, v153
	v_mov_b32_e32 v37, v153
	v_mov_b32_e32 v38, v153
	v_mov_b32_e32 v39, v153
	v_mov_b32_e32 v44, v153
	v_mov_b32_e32 v45, v153
	v_mov_b32_e32 v46, v153
	v_mov_b32_e32 v47, v153
	v_mov_b32_e32 v48, v153
	v_mov_b32_e32 v49, v153
	v_mov_b32_e32 v50, v153
	v_mov_b32_e32 v51, v153
	v_mov_b32_e32 v52, v153
	v_mov_b32_e32 v53, v153
	v_mov_b32_e32 v54, v153
	v_mov_b32_e32 v55, v153
	v_add_u32_e32 v27, v121, v127
	v_lshlrev_b32_e32 v133, 4, v42
	v_lshlrev_b32_e32 v134, 4, v43
	v_lshl_add_u64 v[100:101], s[12:13], 0, v[152:153]
	ds_write_b128 v26, v[140:143] offset:34816
	v_mov_b32_e32 v71, v153
	s_waitcnt vmcnt(0)
	v_mul_f32_e32 v25, v25, v154
	v_mul_f32_e32 v26, v29, v155
	v_mul_f32_e32 v29, v30, v156
	v_mul_f32_e32 v30, v31, v157
	v_mul_f32_e32 v31, v33, v144
	v_mul_f32_e32 v33, v34, v145
	v_mul_f32_e32 v34, v35, v146
	v_mul_f32_e32 v35, v41, v147
	v_cvt_pk_bf16_f32 v140, v25, v26
	v_cvt_pk_bf16_f32 v141, v29, v30
	v_cvt_pk_bf16_f32 v142, v31, v33
	v_cvt_pk_bf16_f32 v143, v34, v35
	ds_write_b128 v27, v[140:143] offset:34816
	s_cmp_eq_u32 s42, s60
	s_cbranch_scc1 .LBB0_183

; #define GM_LOADV(bb_, hh_) do { const size_t t_ = (size_t)(bb_) * 128 + skey; const bf16_t* vp_ = A.Z + t_ * INW + O_G + (hh_) * 128 + 8 * spart; \
;         _Pragma("unroll") for (int i = 0; i < 4; ++i) vr[i] = *(const u32x4*)(vp_ + 32 * i); \
;         pa = *(const f32x4*)(A.VSS + t_ * 32 + 8 * spart); pb = *(const f32x4*)(A.VSS + t_ * 32 + 8 * spart + 4); } while (0)
; __device__ __forceinline__ void conv_load(const ConvJob& J, int idx, f32x4 (&v)[8], int lane) {
;     const bool second = idx >= 32768; const int r = idx & 32767;
;     const float* W = second ? J.w2 : J.w1; const int N = second ? D : FF, nb = second ? 128 : 512;
;     const int k0 = 64 * (r / nb), n0 = 32 * (r % nb);
;     const float* p = W + (size_t)(k0 + 8 * (lane >> 3)) * N + n0 + 4 * (lane & 7);
; #pragma unroll
;     for (int i = 0; i < 8; ++i) v[i] = __builtin_nontemporal_load((const f32x4*)(p + (size_t)i * N));
; __device__ __forceinline__ void gmlp_stream(LAS unsigned char* lds, const MixArgs& A, ConvJob& J, int vcu, int G, int tid, int wid, int lane) {
;     ...
;         const int nu = u + G; const bool nvalid = nu < NU; const int nhh = nu & 15, nbb = nu >> 4;
;         if (nvalid) GM_LOADV(nbb, nhh);
;         f32x4 cv[8]; const int cidx = J.next; const bool cdo = cidx < CONV_BLOCKS;
;         if (cdo) conv_load(J, cidx, cv, lane);
.LBB0_183:
	s_add_i32 s78, s78, s3
	s_cmpk_lt_i32 s78, 0x800
	s_waitcnt lgkmcnt(0)
	s_barrier
	s_cselect_b64 s[50:51], -1, 0
	s_cmpk_gt_i32 s78, 0x7ff
	s_cselect_b64 s[14:15], -1, 0
	s_and_b32 s64, s78, 15
	s_ashr_i32 s12, s78, 4
	s_and_b64 vcc, exec, s[14:15]
	s_cbranch_vccnz .LBB0_185
	s_ashr_i32 s13, s12, 31
	s_lshl_b64 s[4:5], s[12:13], 7
	v_lshl_add_u64 v[0:1], s[4:5], 0, v[148:149]
	v_mov_b64_e32 v[2:3], s[18:19]
	v_mad_u64_u32 v[2:3], s[4:5], v0, s56, v[2:3]
	v_mad_i32_i24 v3, v1, s56, v3
	s_lshl_b32 s6, s64, 8
	v_lshl_add_u64 v[2:3], v[2:3], 0, s[6:7]
	v_mov_b32_e32 v77, v153
	v_lshl_add_u64 v[2:3], v[2:3], 0, v[76:77]
	v_lshl_add_u64 v[4:5], v[2:3], 0, s[8:9]
	v_add_co_u32_e32 v2, vcc, s57, v2
	v_lshlrev_b64 v[0:1], 7, v[0:1]
	s_nop 0
	v_addc_co_u32_e32 v3, vcc, 0, v3, vcc
	global_load_dwordx4 v[12:15], v[4:5], off offset:64
	global_load_dwordx4 v[16:19], v[4:5], off offset:128
	global_load_dwordx4 v[8:11], v[2:3], off offset:2048
	global_load_dwordx4 v[20:23], v[4:5], off offset:192
	v_lshl_add_u64 v[4:5], v[98:99], 0, v[0:1]
	global_load_dwordx4 v[0:3], v[4:5], off offset:16
	s_nop 0
	global_load_dwordx4 v[4:7], v[4:5], off
	s_cmp_eq_u32 s64, s99
	s_cbranch_scc1 .Lgm_vg_skip
	s_lshl_b32 s6, s64, 9
	v_lshl_add_u64 v[250:251], v[100:101], 0, s[6:7]
	global_load_dwordx4 v[218:221], v[250:251], off
	global_load_dwordx4 v[222:225], v[250:251], off offset:16
	global_load_dwordx4 v[226:229], v[250:251], off offset:128
	global_load_dwordx4 v[230:233], v[250:251], off offset:144
	global_load_dwordx4 v[234:237], v[250:251], off offset:256
	global_load_dwordx4 v[238:241], v[250:251], off offset:272
	global_load_dwordx4 v[242:245], v[250:251], off offset:384
	global_load_dwordx4 v[246:249], v[250:251], off offset:400
	s_mov_b32 s99, s64
.Lgm_vg_skip:
.LBB0_185:
	s_cmp_lt_i32 s81, 0x10000
	s_cselect_b64 s[40:41], -1, 0
	s_cmp_gt_i32 s81, 0xffff
	s_cbranch_scc1 .Lgm_nocdo
	s_and_b32 s4, s81, 0x7fff
	s_cmpk_gt_i32 s81, 0x7fff
	s_cselect_b32 s5, s27, s25
	s_cselect_b32 s6, s26, s24
	v_mov_b32_e32 v37, s5
	s_cselect_b32 s5, 7, 9
	v_mov_b32_e32 v36, s6
	s_cselect_b32 s6, s61, 0x1ff
	s_cselect_b32 s13, 12, 14
	s_lshr_b32 s4, s4, s5
	v_lshl_or_b32 v152, s4, 6, v72
	s_and_b32 s4, s6, s81
	v_lshlrev_b64 v[38:39], s13, v[152:153]
	v_lshl_add_u64 v[36:37], v[38:39], 2, v[36:37]
	s_lshl_b32 s6, s4, 7
	v_lshl_add_u64 v[36:37], v[36:37], 0, s[6:7]
	v_lshlrev_b32_e32 v152, 2, v86
	v_lshl_add_u64 v[64:65], v[36:37], 0, v[152:153]
	s_lshl_b64 s[4:5], 1, s13
	v_lshl_add_u64 v[44:45], s[4:5], 2, v[64:65]
	s_lshl_b64 s[4:5], 2, s13
	v_lshl_add_u64 v[48:49], s[4:5], 2, v[64:65]
	s_lshl_b64 s[4:5], 3, s13
	v_lshl_add_u64 v[52:53], s[4:5], 2, v[64:65]
	s_lshl_b64 s[4:5], 4, s13
	v_lshl_add_u64 v[56:57], s[4:5], 2, v[64:65]
	s_lshl_b64 s[4:5], 5, s13
	v_lshl_add_u64 v[60:61], s[4:5], 2, v[64:65]
	s_lshl_b64 s[4:5], 6, s13
	v_lshl_add_u64 v[66:67], s[4:5], 2, v[64:65]
	s_lshl_b64 s[4:5], 7, s13
	v_lshl_add_u64 v[68:69], s[4:5], 2, v[64:65]
	global_load_dwordx4 v[36:39], v[64:65], off nt
	s_nop 0
	global_load_dwordx4 v[44:47], v[44:45], off nt
	s_nop 0
	global_load_dwordx4 v[48:51], v[48:49], off nt
	s_nop 0
	global_load_dwordx4 v[52:55], v[52:53], off nt
	s_nop 0
	global_load_dwordx4 v[56:59], v[56:57], off nt
	s_nop 0
	global_load_dwordx4 v[60:63], v[60:61], off nt
	s_nop 0
	global_load_dwordx4 v[64:67], v[66:67], off nt
	s_nop 0
	global_load_dwordx4 v[68:71], v[68:69], off nt

; __global__ void __launch_bounds__(NWAVES * 64, 2) fwd_mega(Args args) {
	.amdhsa_kernel _Z8fwd_mega4Args
		.amdhsa_group_segment_fixed_size 0
		.amdhsa_private_segment_fixed_size 0
		.amdhsa_kernarg_size 408
		.amdhsa_user_sgpr_count 2
		.amdhsa_user_sgpr_dispatch_ptr 0
		.amdhsa_user_sgpr_queue_ptr 0
		.amdhsa_user_sgpr_kernarg_segment_ptr 1
		.amdhsa_user_sgpr_dispatch_id 0
		.amdhsa_user_sgpr_kernarg_preload_length 0
		.amdhsa_user_sgpr_kernarg_preload_offset 0
		.amdhsa_user_sgpr_private_segment_size 0
		.amdhsa_uses_dynamic_stack 0
		.amdhsa_enable_private_segment 0
		.amdhsa_system_sgpr_workgroup_id_x 1
		.amdhsa_system_sgpr_workgroup_id_y 0
		.amdhsa_system_sgpr_workgroup_id_z 0
		.amdhsa_system_sgpr_workgroup_info 0
		.amdhsa_system_vgpr_workitem_id 2
		.amdhsa_next_free_vgpr 256
		.amdhsa_next_free_sgpr 102
		.amdhsa_accum_offset 256
		.amdhsa_reserve_vcc 1
		.amdhsa_float_round_mode_32 0
		.amdhsa_float_round_mode_16_64 0
		.amdhsa_float_denorm_mode_32 3
		.amdhsa_float_denorm_mode_16_64 3
		.amdhsa_dx10_clamp 1
		.amdhsa_ieee_mode 1
		.amdhsa_fp16_overflow 0
		.amdhsa_tg_split 0
		.amdhsa_exception_fp_ieee_invalid_op 0
		.amdhsa_exception_fp_denorm_src 0
		.amdhsa_exception_fp_ieee_div_zero 0
		.amdhsa_exception_fp_ieee_overflow 0
		.amdhsa_exception_fp_ieee_underflow 0
		.amdhsa_exception_fp_ieee_inexact 0
		.amdhsa_exception_int_div_zero 0
	.end_amdhsa_kernel

; __global__ void __launch_bounds__(NWAVES * 64, 2) fwd_mega(Args args) {
amdhsa.kernels:
  - .agpr_count:     0
    .args:
      - .offset:         0
        .size:           152
        .value_kind:     by_value
      - .offset:         152
        .size:           4
        .value_kind:     hidden_block_count_x
      - .offset:         156
        .size:           4
        .value_kind:     hidden_block_count_y
      - .offset:         160
        .size:           4
        .value_kind:     hidden_block_count_z
      - .offset:         164
        .size:           2
        .value_kind:     hidden_group_size_x
      - .offset:         166
        .size:           2
        .value_kind:     hidden_group_size_y
      - .offset:         168
        .size:           2
        .value_kind:     hidden_group_size_z
      - .offset:         170
        .size:           2
        .value_kind:     hidden_remainder_x
      - .offset:         172
        .size:           2
        .value_kind:     hidden_remainder_y
      - .offset:         174
        .size:           2
        .value_kind:     hidden_remainder_z
      - .offset:         192
        .size:           8
        .value_kind:     hidden_global_offset_x
      - .offset:         200
        .size:           8
        .value_kind:     hidden_global_offset_y
      - .offset:         208
        .size:           8
        .value_kind:     hidden_global_offset_z
      - .offset:         216
        .size:           2
        .value_kind:     hidden_grid_dims
      - .offset:         240
        .size:           8
        .value_kind:     hidden_multigrid_sync_arg
      - .offset:         272
        .size:           4
        .value_kind:     hidden_dynamic_lds_size
    .group_segment_fixed_size: 0
    .kernarg_segment_align: 8
    .kernarg_segment_size: 408
    .language:       OpenCL C
    .language_version:
      - 2
      - 0
    .max_flat_workgroup_size: 512
    .name:           _Z8fwd_mega4Args
    .private_segment_fixed_size: 0
    .sgpr_count:     108
    .sgpr_spill_count: 0
    .symbol:         _Z8fwd_mega4Args.kd
    .uniform_work_group_size: 1
    .uses_dynamic_stack: false
    .vgpr_count:     256
    .vgpr_spill_count: 0
    .wavefront_size: 64
